# loop-edge rotation (asm guide 7.11): attention loop's counter update, row-sum update and back-edge moved ahead of the per-tile barrier; exit path gets its own barrier copy
# speedup vs baseline: 1.0021x; 1.0021x over previous
; #define SBAR() __builtin_amdgcn_sched_barrier(0)
; #define TILE_BAR(n) do { asm volatile("s_waitcnt vmcnt(" #n ")" ::: "memory"); __builtin_amdgcn_s_barrier(); asm volatile("" ::: "memory"); } while (0)
; #define RESC(a) do { if (__any((a) < 1.f)) { if (hi == 0) al_l[r32] = (a); asm volatile("s_waitcnt lgkmcnt(0)" ::: "memory"); \
;     for (int d = 0; d < 4; ++d) for (int r = 0; r < 16; ++r) o[d][r] *= al_l[crow(r, hi)]; } } while (0)
; __device__ __forceinline__ void attn_unit(const bf16* __restrict__ Qb, const bf16* __restrict__ Kh, const bf16* __restrict__ Vh, int klat0, int nlt, int kctx0, int NT,
;                                           float lam, float post, const float* __restrict__ subw, bf16* __restrict__ Ob, char* lds) {
;     ...
;     for (int j = 1; j + 1 < NT; j += 2) {
;       if (j + 2 < NT) DMA_TILE(j + 2);
;       SBAR(); qkt(pB0, pB1, KS(j), qr, r32, hi, sb);
;       finishSM(pA0, pA1, alA, l_reg, pa0, pa1, pa2, pa3); SBAR();
;       pv_d0(o, VB(j - 1), pa0, pa1, pa2, pa3); partialSM(pB0, pB1, m_reg, mnB, alB);
;       RESC(alB);
;       if (j + 2 < NT) TILE_BAR(4); else TILE_BAR(0);
;       if (j + 3 < NT) DMA_TILE(j + 3);
;       SBAR(); qkt(pA0, pA1, KS(j + 1), qr, r32, hi, sb);
;       finishSM(pB0, pB1, alB, l_reg, pa0, pa1, pa2, pa3); SBAR();
;       pv_d0(o, VB(j), pa0, pa1, pa2, pa3); partialSM(pA0, pA1, m_reg, mnA, alA);
;       RESC(alA);
;       if (j + 3 < NT) TILE_BAR(4); else TILE_BAR(0);
;     }
;     ...
;   SBAR(); qkt(pB0, pB1, KS(NT - 1), qr, r32, hi, sb);
;   finishSM(pA0, pA1, alA, l_reg, pa0, pa1, pa2, pa3); SBAR();
;   pv_d0(o, VB(NT - 2), pa0, pa1, pa2, pa3); partialSM(pB0, pB1, m_reg, mnB, alB);
.LBB0_780:
	v_add_f32_e32 v82, v130, v131
	v_fmac_f32_e32 v82, v173, v163
	v_add_f32_e32 v163, v99, v100
	v_fmac_f32_e32 v163, v82, v132
	s_add_i32 s36, s36, 0x8000
	s_and_b64 vcc, exec, s[10:11]
	s_cbranch_vccnz .Lmy_last
	s_mov_b32 s12, s37
	v_mov_b32_e32 v173, v205
	s_waitcnt vmcnt(4)
	s_barrier
	s_branch .LBB0_770
.Lmy_last:
	s_waitcnt vmcnt(0)
	s_barrier
.LBB0_786:
	v_mov_b64_e32 v[106:107], v[80:81]
	v_mov_b32_e32 v109, v204
	v_mov_b32_e32 v108, v202
	v_mov_b32_e32 v111, v201
	v_mov_b32_e32 v110, v198
	v_mov_b32_e32 v113, v197
	v_mov_b32_e32 v112, v194
	v_mov_b32_e32 v135, v193
	v_mov_b32_e32 v134, v176
	v_mov_b32_e32 v136, v203
	v_mov_b32_e32 v133, v200
	v_mov_b32_e32 v137, v199
	v_mov_b32_e32 v132, v196
	v_mov_b32_e32 v213, v195
	v_mov_b32_e32 v131, v192
	v_mov_b32_e32 v215, v177
	v_mov_b32_e32 v214, v175
	v_mov_b64_e32 v[104:105], v[78:79]
	v_mov_b64_e32 v[102:103], v[76:77]
	v_mov_b64_e32 v[100:101], v[74:75]
	v_mov_b64_e32 v[98:99], v[72:73]
	v_mov_b64_e32 v[96:97], v[70:71]
	v_mov_b64_e32 v[94:95], v[68:69]
	v_mov_b64_e32 v[92:93], v[66:67]
	v_mov_b32_e32 v206, v174
